# skinny NC=1 GEMM loops (attn Wo, HGRN Wo, FFN2): fragment reads issued ahead + counted lgkmcnt, counted vmcnt before LDS staging; on top of v036
# baseline (speedup 1.0000x reference)
; #define SK_LOAD3() do { SK_LOAD(0, 0); if (1 < nsc) SK_LOAD(1, 1); if (2 < nsc) SK_LOAD(2, 2); } while (0)
; #define SK_WRITE(s_, b) do { LAS unsigned char* bb = lds + (b) * BUF; _Pragma("unroll") for (int i = 0; i < 4; ++i) *(LAS bf16x8*)(bb + st0 + i * 8192) = ra[s_][i]; \
;         _Pragma("unroll") for (int i = 0; i < NW2; ++i) *(LAS bf16x8*)(bb + 32768 + st0 + i * 8192) = rw[s_][i]; } while (0)
; template <class Epi, int NC>
; __device__ __forceinline__ void skinny_phase(const bf16* __restrict__ A, int lda, int a_goff, const bf16* __restrict__ Bt, int ldb, int K, int ncg, int vcu, int G, const Epi& E, LAS float* rs_tab, LAS unsigned char* lds) {
;     ...
;     int u = vcu;
;     if (u < NU) { SK_PTRS(u); SK_LOAD3(); }
; #pragma unroll 1
;     while (u < NU) {
;         const int cg = (u >> 2) * NC, rb = u & 3;
;         f32x16 acc[NC] = {};
;         SK_WRITE(0, 0);
;         asm volatile("s_waitcnt lgkmcnt(0)" ::: "memory"); __builtin_amdgcn_s_barrier(); asm volatile("" ::: "memory");
; #pragma unroll 1
;         for (int c3 = 0; c3 < nsc; c3 += 3) { SK_STEP(0); SK_STEP(1); SK_STEP(2); }
.LBB0_627:
	s_waitcnt vmcnt(6) lgkmcnt(0)
	ds_write_b128 v107, v[20:23]
	ds_write_b128 v107, v[24:27] offset:8192
	ds_write_b128 v107, v[32:35] offset:16384
	ds_write_b128 v107, v[36:39] offset:24576
	ds_write_b128 v107, v[44:47] offset:32768
	ds_write_b128 v107, v[48:51] offset:40960
	s_waitcnt lgkmcnt(0)
	s_barrier
	v_mov_b32_e32 v4, v3
	v_mov_b32_e32 v5, v3
	v_mov_b32_e32 v6, v3
	v_mov_b32_e32 v7, v3
	v_mov_b32_e32 v8, v3
	v_mov_b32_e32 v9, v3
	v_mov_b32_e32 v10, v3
	v_mov_b32_e32 v11, v3
	v_mov_b32_e32 v12, v3
	v_mov_b32_e32 v13, v3
	v_mov_b32_e32 v14, v3
	v_mov_b32_e32 v15, v3
	v_mov_b32_e32 v16, v3
	v_mov_b32_e32 v17, v3
	v_mov_b32_e32 v2, v3
	v_mov_b64_e32 v[18:19], v[16:17]
	s_mov_b32 s4, s65
	s_mov_b32 s5, 0
	s_mov_b64 s[20:21], 0
	v_mov_b64_e32 v[16:17], v[14:15]
	v_mov_b64_e32 v[14:15], v[12:13]
	v_mov_b64_e32 v[12:13], v[10:11]
	v_mov_b64_e32 v[10:11], v[8:9]
	v_mov_b64_e32 v[8:9], v[6:7]
	v_mov_b64_e32 v[6:7], v[4:5]
	v_mov_b64_e32 v[4:5], v[2:3]
.LBB0_628:
	s_and_b32 s7, 1, s5
	s_cselect_b32 s6, 0, 0xc000
	s_add_i32 s6, s6, 0
	s_cmp_lt_u32 s5, 5
	s_cselect_b64 s[40:41], -1, 0
	s_cmp_gt_u32 s5, 4
	s_cselect_b64 s[36:37], -1, 0
	v_add_u32_e32 v2, s6, v105
	s_and_b64 vcc, exec, s[36:37]
	s_cmp_lt_u32 s5, 6
	s_cbranch_scc1 .Lsk627_a
	s_waitcnt vmcnt(0)
.Lsk627_a:
	s_waitcnt vmcnt(4)
	ds_write_b128 v2, v[28:31]
	ds_write_b128 v2, v[40:43] offset:8192
	ds_write_b128 v2, v[56:59] offset:16384
	ds_write_b128 v2, v[60:63] offset:24576
	ds_write_b128 v2, v[68:71] offset:32768
	ds_write_b128 v2, v[72:75] offset:40960
	s_cbranch_vccnz .LBB0_630
	v_lshl_add_u64 v[32:33], v[98:99], 0, s[20:21]
	v_add_co_u32_e32 v24, vcc, 0x10000, v32
	v_lshl_add_u64 v[44:45], v[94:95], 0, s[20:21]
	s_nop 0
	v_addc_co_u32_e32 v25, vcc, 0, v33, vcc
	v_add_co_u32_e32 v34, vcc, 0x20000, v32
	v_lshl_add_u64 v[48:49], v[96:97], 0, s[20:21]
	s_nop 0
	v_addc_co_u32_e32 v35, vcc, 0, v33, vcc
	v_add_co_u32_e32 v36, vcc, 0x30000, v32
	global_load_dwordx4 v[20:23], v[32:33], off offset:1536
	s_nop 0
	global_load_dwordx4 v[24:27], v[24:25], off offset:1536
	v_addc_co_u32_e32 v37, vcc, 0, v33, vcc
	global_load_dwordx4 v[32:35], v[34:35], off offset:1536
	s_nop 0
	global_load_dwordx4 v[36:39], v[36:37], off offset:1536
	s_nop 0
	global_load_dwordx4 v[44:47], v[44:45], off offset:1536
	s_nop 0
	global_load_dwordx4 v[48:51], v[48:49], off offset:1536
.LBB0_630:
	s_cmp_eq_u32 s7, 1
	s_cselect_b32 s7, 0xc000, 0
	s_add_i32 s7, s7, 0
	v_add_u32_e32 v210, s7, v108
	v_add_u32_e32 v211, s7, v109
	s_cmpk_eq_i32 s20, 0xc00
	v_add_u32_e32 v208, v210, v112
	ds_read_b128 v[216:219], v208
	v_add_u32_e32 v209, v211, v112
	ds_read_b128 v[232:235], v209 offset:32768
	v_add_u32_e32 v208, v210, v113
	ds_read_b128 v[220:223], v208
	v_add_u32_e32 v209, v211, v113
	ds_read_b128 v[236:239], v209 offset:32768
	v_add_u32_e32 v208, v210, v114
	ds_read_b128 v[224:227], v208
	v_add_u32_e32 v209, v211, v114
	ds_read_b128 v[240:243], v209 offset:32768
	v_add_u32_e32 v208, v210, v115
	ds_read_b128 v[228:231], v208
	v_add_u32_e32 v209, v211, v115
	ds_read_b128 v[244:247], v209 offset:32768
	s_waitcnt lgkmcnt(6)
	v_mfma_f32_32x32x16_bf16 v[4:19], v[232:235], v[216:219], v[4:19]
	s_waitcnt lgkmcnt(4)
	v_mfma_f32_32x32x16_bf16 v[4:19], v[236:239], v[220:223], v[4:19]
	s_waitcnt lgkmcnt(2)
	v_mfma_f32_32x32x16_bf16 v[4:19], v[240:243], v[224:227], v[4:19]
	s_waitcnt lgkmcnt(0)
	s_barrier
	v_mfma_f32_32x32x16_bf16 v[4:19], v[244:247], v[228:231], v[4:19]
	s_cbranch_scc1 .LBB0_632
	v_add_u32_e32 v120, s7, v105
	s_waitcnt vmcnt(6)
	ds_write_b128 v120, v[52:55]
	ds_write_b128 v120, v[64:67] offset:8192
	ds_write_b128 v120, v[76:79] offset:16384
	ds_write_b128 v120, v[80:83] offset:24576
	ds_write_b128 v120, v[84:87] offset:32768
	ds_write_b128 v120, v[88:91] offset:40960

.LBB0_634:
	v_add_u32_e32 v212, s6, v108
	v_add_u32_e32 v213, s6, v109
	s_add_i32 s6, s5, 3
	s_cmp_gt_u32 s5, 5
	v_add_u32_e32 v208, v212, v112
	ds_read_b128 v[216:219], v208
	v_add_u32_e32 v209, v213, v112
	ds_read_b128 v[232:235], v209 offset:32768
	v_add_u32_e32 v208, v212, v113
	ds_read_b128 v[220:223], v208
	v_add_u32_e32 v209, v213, v113
	ds_read_b128 v[236:239], v209 offset:32768
	v_add_u32_e32 v208, v212, v114
	ds_read_b128 v[224:227], v208
	v_add_u32_e32 v209, v213, v114
	ds_read_b128 v[240:243], v209 offset:32768
	v_add_u32_e32 v208, v212, v115
	ds_read_b128 v[228:231], v208
	v_add_u32_e32 v209, v213, v115
	ds_read_b128 v[244:247], v209 offset:32768
	s_waitcnt lgkmcnt(6)
	v_mfma_f32_32x32x16_bf16 v[4:19], v[232:235], v[216:219], v[4:19]
	s_waitcnt lgkmcnt(4)
	v_mfma_f32_32x32x16_bf16 v[4:19], v[236:239], v[220:223], v[4:19]
	s_waitcnt lgkmcnt(2)
	v_mfma_f32_32x32x16_bf16 v[4:19], v[240:243], v[224:227], v[4:19]
	s_waitcnt lgkmcnt(0)
	s_barrier
	v_mfma_f32_32x32x16_bf16 v[4:19], v[244:247], v[228:231], v[4:19]
	s_cbranch_scc1 .LBB0_640
	s_andn2_b64 vcc, exec, s[40:41]
	s_cbranch_vccnz .LBB0_637
	s_bitcmp1_b32 s6, 0
	s_cselect_b32 s7, 0xc000, 0
	v_add_u32_e32 v120, s7, v107
	s_waitcnt vmcnt(6)
	ds_write_b128 v120, v[20:23]
	ds_write_b128 v120, v[24:27] offset:8192
	ds_write_b128 v120, v[32:35] offset:16384
	ds_write_b128 v120, v[36:39] offset:24576
	ds_write_b128 v120, v[44:47] offset:32768
	ds_write_b128 v120, v[48:51] offset:40960

.LBB0_639:
	v_add_u32_e32 v208, v210, v112
	ds_read_b128 v[216:219], v208
	v_add_u32_e32 v209, v211, v112
	ds_read_b128 v[232:235], v209 offset:32768
	v_add_u32_e32 v208, v210, v113
	ds_read_b128 v[220:223], v208
	v_add_u32_e32 v209, v211, v113
	ds_read_b128 v[236:239], v209 offset:32768
	v_add_u32_e32 v208, v210, v114
	ds_read_b128 v[224:227], v208
	v_add_u32_e32 v209, v211, v114
	ds_read_b128 v[240:243], v209 offset:32768
	v_add_u32_e32 v208, v210, v115
	ds_read_b128 v[228:231], v208
	v_add_u32_e32 v209, v211, v115
	ds_read_b128 v[244:247], v209 offset:32768
	s_waitcnt lgkmcnt(6)
	v_mfma_f32_32x32x16_bf16 v[4:19], v[232:235], v[216:219], v[4:19]
	s_waitcnt lgkmcnt(4)
	v_mfma_f32_32x32x16_bf16 v[4:19], v[236:239], v[220:223], v[4:19]
	s_waitcnt lgkmcnt(2)
	v_mfma_f32_32x32x16_bf16 v[4:19], v[240:243], v[224:227], v[4:19]
	s_waitcnt lgkmcnt(0)
	s_barrier
	v_mfma_f32_32x32x16_bf16 v[4:19], v[244:247], v[228:231], v[4:19]

; #define SK_LOAD3() do { SK_LOAD(0, 0); if (1 < nsc) SK_LOAD(1, 1); if (2 < nsc) SK_LOAD(2, 2); } while (0)
; #define SK_WRITE(s_, b) do { LAS unsigned char* bb = lds + (b) * BUF; _Pragma("unroll") for (int i = 0; i < 4; ++i) *(LAS bf16x8*)(bb + st0 + i * 8192) = ra[s_][i]; \
;         _Pragma("unroll") for (int i = 0; i < NW2; ++i) *(LAS bf16x8*)(bb + 32768 + st0 + i * 8192) = rw[s_][i]; } while (0)
; template <class Epi, int NC>
; __device__ __forceinline__ void skinny_phase(const bf16* __restrict__ A, int lda, int a_goff, const bf16* __restrict__ Bt, int ldb, int K, int ncg, int vcu, int G, const Epi& E, LAS float* rs_tab, LAS unsigned char* lds) {
;     ...
;     int u = vcu;
;     if (u < NU) { SK_PTRS(u); SK_LOAD3(); }
; #pragma unroll 1
;     while (u < NU) {
;         const int cg = (u >> 2) * NC, rb = u & 3;
;         f32x16 acc[NC] = {};
;         SK_WRITE(0, 0);
;         asm volatile("s_waitcnt lgkmcnt(0)" ::: "memory"); __builtin_amdgcn_s_barrier(); asm volatile("" ::: "memory");
; #pragma unroll 1
;         for (int c3 = 0; c3 < nsc; c3 += 3) { SK_STEP(0); SK_STEP(1); SK_STEP(2); }
.LBB0_2801:
	s_waitcnt vmcnt(6) lgkmcnt(0)
	ds_write_b128 v107, v[20:23]
	ds_write_b128 v107, v[32:35] offset:8192
	ds_write_b128 v107, v[60:63] offset:16384
	ds_write_b128 v107, v[48:51] offset:24576
	ds_write_b128 v107, v[72:75] offset:32768
	ds_write_b128 v107, v[80:83] offset:40960
	s_waitcnt lgkmcnt(0)
	s_barrier
	v_mov_b32_e32 v4, v3
	v_mov_b32_e32 v5, v3
	v_mov_b32_e32 v6, v3
	v_mov_b32_e32 v7, v3
	v_mov_b32_e32 v8, v3
	v_mov_b32_e32 v9, v3
	v_mov_b32_e32 v10, v3
	v_mov_b32_e32 v11, v3
	v_mov_b32_e32 v12, v3
	v_mov_b32_e32 v13, v3
	v_mov_b32_e32 v14, v3
	v_mov_b32_e32 v15, v3
	v_mov_b32_e32 v16, v3
	v_mov_b32_e32 v17, v3
	v_mov_b32_e32 v2, v3
	v_mov_b64_e32 v[18:19], v[16:17]
	s_mov_b32 s4, s62
	s_mov_b32 s5, 0
	s_mov_b64 s[20:21], 0
	v_mov_b64_e32 v[16:17], v[14:15]
	v_mov_b64_e32 v[14:15], v[12:13]
	v_mov_b64_e32 v[12:13], v[10:11]
	v_mov_b64_e32 v[10:11], v[8:9]
	v_mov_b64_e32 v[8:9], v[6:7]
	v_mov_b64_e32 v[6:7], v[4:5]
	v_mov_b64_e32 v[4:5], v[2:3]
.LBB0_2802:
	s_add_i32 s6, s5, 1
	s_cmp_lt_u32 s5, 21
	s_cselect_b64 s[42:43], -1, 0
	s_cmp_gt_u32 s5, 20
	s_cbranch_scc1 .LBB0_2804
	s_bitcmp1_b32 s6, 0
	s_cselect_b32 s7, 0xc000, 0
	v_add_u32_e32 v2, s7, v107
	s_waitcnt vmcnt(4)
	ds_write_b128 v2, v[24:27]
	ds_write_b128 v2, v[28:31] offset:8192
	ds_write_b128 v2, v[56:59] offset:16384
	ds_write_b128 v2, v[44:47] offset:24576
	ds_write_b128 v2, v[68:71] offset:32768
	ds_write_b128 v2, v[76:79] offset:40960
.LBB0_2804:
	s_cmp_lt_u32 s5, 19
	s_cselect_b64 s[40:41], -1, 0
	s_cmp_gt_u32 s5, 18
	s_cselect_b64 s[36:37], -1, 0
	s_and_b64 vcc, exec, s[36:37]
	s_cbranch_vccnz .LBB0_2806
	s_waitcnt vmcnt(12)
	v_lshl_add_u64 v[48:49], v[94:95], 0, s[20:21]
	v_add_co_u32_e32 v32, vcc, 0x2c000, v48
	v_lshl_add_u64 v[72:73], v[96:97], 0, s[20:21]
	s_nop 0
	v_addc_co_u32_e32 v33, vcc, 0, v49, vcc
	v_add_co_u32_e32 v50, vcc, 0x58000, v48
	global_load_dwordx4 v[20:23], v[48:49], off offset:1536
	s_nop 0
	global_load_dwordx4 v[32:35], v[32:33], off offset:1536
	v_addc_co_u32_e32 v51, vcc, 0, v49, vcc
	v_add_co_u32_e32 v48, vcc, 0x84000, v48
	v_lshl_add_u64 v[80:81], v[92:93], 0, s[20:21]
	s_nop 0
	v_addc_co_u32_e32 v49, vcc, 0, v49, vcc
	global_load_dwordx4 v[60:63], v[50:51], off offset:1536
	s_nop 0
	global_load_dwordx4 v[48:51], v[48:49], off offset:1536
	s_nop 0
	global_load_dwordx4 v[72:75], v[72:73], off offset:1536
	s_nop 0
	global_load_dwordx4 v[80:83], v[80:81], off offset:1536
.LBB0_2806:
	s_bitcmp1_b32 s5, 0
	s_cselect_b32 s7, 0xc000, 0
	s_add_i32 s7, s7, 0
	v_add_u32_e32 v210, s7, v108
	v_add_u32_e32 v211, s7, v109
	s_andn2_b64 vcc, exec, s[42:43]
	v_add_u32_e32 v208, v210, v112
	ds_read_b128 v[216:219], v208
	v_add_u32_e32 v209, v211, v112
	ds_read_b128 v[232:235], v209 offset:32768
	v_add_u32_e32 v208, v210, v113
	ds_read_b128 v[220:223], v208
	v_add_u32_e32 v209, v211, v113
	ds_read_b128 v[236:239], v209 offset:32768
	v_add_u32_e32 v208, v210, v114
	ds_read_b128 v[224:227], v208
	v_add_u32_e32 v209, v211, v114
	ds_read_b128 v[240:243], v209 offset:32768
	v_add_u32_e32 v208, v210, v115
	ds_read_b128 v[228:231], v208
	v_add_u32_e32 v209, v211, v115
	ds_read_b128 v[244:247], v209 offset:32768
	s_waitcnt lgkmcnt(6)
	v_mfma_f32_32x32x16_bf16 v[4:19], v[232:235], v[216:219], v[4:19]
	s_waitcnt lgkmcnt(4)
	v_mfma_f32_32x32x16_bf16 v[4:19], v[236:239], v[220:223], v[4:19]
	s_waitcnt lgkmcnt(2)
	v_mfma_f32_32x32x16_bf16 v[4:19], v[240:243], v[224:227], v[4:19]
	s_waitcnt lgkmcnt(0)
	s_barrier
	v_mfma_f32_32x32x16_bf16 v[4:19], v[244:247], v[228:231], v[4:19]
	s_cbranch_vccnz .LBB0_2813
	s_cmpk_eq_i32 s20, 0x2800
	s_cbranch_scc1 .LBB0_2809
	v_add_u32_e32 v120, s7, v105
	s_waitcnt vmcnt(6)
	ds_write_b128 v120, v[36:39]
	ds_write_b128 v120, v[40:43] offset:8192
	ds_write_b128 v120, v[52:55] offset:16384
	ds_write_b128 v120, v[64:67] offset:24576
	ds_write_b128 v120, v[84:87] offset:32768
	ds_write_b128 v120, v[88:91] offset:40960
.LBB0_2809:
	s_cmp_gt_u32 s5, 17
	s_cbranch_scc1 .LBB0_2811
	s_waitcnt vmcnt(12)
	v_lshl_add_u64 v[44:45], v[94:95], 0, s[20:21]
	v_add_co_u32_e32 v28, vcc, 0x2c000, v44
	v_lshl_add_u64 v[68:69], v[96:97], 0, s[20:21]
	s_nop 0
	v_addc_co_u32_e32 v29, vcc, 0, v45, vcc
	v_add_co_u32_e32 v46, vcc, 0x58000, v44
	global_load_dwordx4 v[24:27], v[44:45], off offset:2048
	s_nop 0
	global_load_dwordx4 v[28:31], v[28:29], off offset:2048
	v_addc_co_u32_e32 v47, vcc, 0, v45, vcc
	v_add_co_u32_e32 v44, vcc, 0x84000, v44
	v_lshl_add_u64 v[76:77], v[92:93], 0, s[20:21]
	s_nop 0
	v_addc_co_u32_e32 v45, vcc, 0, v45, vcc
	global_load_dwordx4 v[56:59], v[46:47], off offset:2048
	s_nop 0
	global_load_dwordx4 v[44:47], v[44:45], off offset:2048
	s_nop 0
	global_load_dwordx4 v[68:71], v[68:69], off offset:2048
	s_nop 0
	global_load_dwordx4 v[76:79], v[76:77], off offset:2048
.LBB0_2811:
	s_bitcmp1_b32 s6, 0
	s_cselect_b32 s6, 0xc000, 0
	s_add_i32 s6, s6, 0
	v_add_u32_e32 v212, s6, v108
	v_add_u32_e32 v213, s6, v109
	v_add_u32_e32 v208, v212, v112
	ds_read_b128 v[216:219], v208
	v_add_u32_e32 v209, v213, v112
	ds_read_b128 v[232:235], v209 offset:32768
	v_add_u32_e32 v208, v212, v113
	ds_read_b128 v[220:223], v208
	v_add_u32_e32 v209, v213, v113
	ds_read_b128 v[236:239], v209 offset:32768
	v_add_u32_e32 v208, v212, v114
	ds_read_b128 v[224:227], v208
	v_add_u32_e32 v209, v213, v114
	ds_read_b128 v[240:243], v209 offset:32768
	v_add_u32_e32 v208, v212, v115
	ds_read_b128 v[228:231], v208
	v_add_u32_e32 v209, v213, v115
	ds_read_b128 v[244:247], v209 offset:32768
	s_waitcnt lgkmcnt(6)
	v_mfma_f32_32x32x16_bf16 v[4:19], v[232:235], v[216:219], v[4:19]
	s_waitcnt lgkmcnt(4)
	v_mfma_f32_32x32x16_bf16 v[4:19], v[236:239], v[220:223], v[4:19]
	s_waitcnt lgkmcnt(2)
	v_mfma_f32_32x32x16_bf16 v[4:19], v[240:243], v[224:227], v[4:19]
	s_waitcnt lgkmcnt(0)
	s_barrier
	v_mfma_f32_32x32x16_bf16 v[4:19], v[244:247], v[228:231], v[4:19]
	s_add_i32 s6, s5, 3
	s_cmp_gt_u32 s5, 19
	s_cbranch_scc0 .LBB0_2814

.LBB0_2814:
	s_andn2_b64 vcc, exec, s[40:41]
	s_cbranch_vccnz .LBB0_2816
	s_bitcmp1_b32 s6, 0
	s_cselect_b32 s7, 0xc000, 0
	v_add_u32_e32 v120, s7, v107
	s_cmp_lt_u32 s5, 18
	s_cbranch_scc1 .Lsk2801_c
	s_waitcnt vmcnt(0)
.Lsk2801_c:
	s_waitcnt vmcnt(6)
	ds_write_b128 v120, v[20:23]
	ds_write_b128 v120, v[32:35] offset:8192
	ds_write_b128 v120, v[60:63] offset:16384
	ds_write_b128 v120, v[48:51] offset:24576
	ds_write_b128 v120, v[72:75] offset:32768
	ds_write_b128 v120, v[80:83] offset:40960
.LBB0_2816:
	s_cmp_gt_u32 s5, 16
	s_cbranch_scc1 .LBB0_2818
	s_waitcnt vmcnt(12)
	v_lshl_add_u64 v[52:53], v[94:95], 0, s[20:21]
	v_add_co_u32_e32 v40, vcc, 0x2c000, v52
	v_lshl_add_u64 v[84:85], v[96:97], 0, s[20:21]
	s_nop 0
	v_addc_co_u32_e32 v41, vcc, 0, v53, vcc
	v_add_co_u32_e32 v54, vcc, 0x58000, v52
	v_lshl_add_u64 v[88:89], v[92:93], 0, s[20:21]
	s_nop 0
	v_addc_co_u32_e32 v55, vcc, 0, v53, vcc
	v_add_co_u32_e32 v64, vcc, 0x84000, v52
	global_load_dwordx4 v[36:39], v[52:53], off offset:2560
	s_nop 0
	global_load_dwordx4 v[40:43], v[40:41], off offset:2560
	v_addc_co_u32_e32 v65, vcc, 0, v53, vcc
	global_load_dwordx4 v[52:55], v[54:55], off offset:2560
	s_nop 0
	global_load_dwordx4 v[64:67], v[64:65], off offset:2560
	s_nop 0
	global_load_dwordx4 v[84:87], v[84:85], off offset:2560
	s_nop 0
	global_load_dwordx4 v[88:91], v[88:89], off offset:2560
.LBB0_2818:
	v_add_u32_e32 v208, v210, v112
	ds_read_b128 v[216:219], v208
	v_add_u32_e32 v209, v211, v112
	ds_read_b128 v[232:235], v209 offset:32768
	v_add_u32_e32 v208, v210, v113
	ds_read_b128 v[220:223], v208
	v_add_u32_e32 v209, v211, v113
	ds_read_b128 v[236:239], v209 offset:32768
	v_add_u32_e32 v208, v210, v114
	ds_read_b128 v[224:227], v208
	v_add_u32_e32 v209, v211, v114
	ds_read_b128 v[240:243], v209 offset:32768
	v_add_u32_e32 v208, v210, v115
	ds_read_b128 v[228:231], v208
	v_add_u32_e32 v209, v211, v115
	ds_read_b128 v[244:247], v209 offset:32768
	s_waitcnt lgkmcnt(6)
	v_mfma_f32_32x32x16_bf16 v[4:19], v[232:235], v[216:219], v[4:19]
	s_waitcnt lgkmcnt(4)
	v_mfma_f32_32x32x16_bf16 v[4:19], v[236:239], v[220:223], v[4:19]
	s_waitcnt lgkmcnt(2)
	v_mfma_f32_32x32x16_bf16 v[4:19], v[240:243], v[224:227], v[4:19]
	s_waitcnt lgkmcnt(0)
	s_barrier
	v_mfma_f32_32x32x16_bf16 v[4:19], v[244:247], v[228:231], v[4:19]
	s_add_u32 s20, s20, 0x600
	s_addc_u32 s21, s21, 0
	s_and_b64 vcc, exec, s[36:37]
	s_cbranch_vccnz .LBB0_2820
